# P0: odd workgroups run the rope/ss-zero tail first and the weight/x copies second (ALU-heavy and memory-bound parts overlap chip-wide)
# speedup vs baseline: 1.0069x; 1.0020x over previous
.LBB0_10:
	s_or_b64 exec, exec, s[2:3]
	s_load_dwordx16 s[72:87], s[0:1], 0x40
	v_readlane_b32 s0, v254, 5
	s_lshr_b32 s89, s0, 6
	v_readlane_b32 s0, v254, 9
	v_readlane_b32 s1, v254, 10
	v_readlane_b32 s2, v254, 11
	v_readlane_b32 s3, v254, 12
	s_cmp_lt_i32 s0, 1
	s_cselect_b64 s[2:3], -1, 0
	s_cmp_gt_i32 s1, 0
	s_cselect_b64 s[0:1], -1, 0
	v_writelane_b32 v254, s2, 31
	s_and_b64 s[6:7], s[2:3], s[0:1]
	s_andn2_b64 vcc, exec, s[6:7]
	v_and_b32_e32 v227, 63, v226
	v_writelane_b32 v254, s3, 32
	s_cbranch_vccnz .LBB0_183
	s_mov_b32 s99, 0
	s_bitcmp1_b32 s88, 0
	s_cbranch_scc0 .Lp0_front
	s_mov_b32 s99, 1
	s_branch .LBB0_163
.Lp0_front:
	s_lshl_b32 s0, s88, 3
	s_add_i32 s8, s89, s0
	s_lshl_b32 s10, s90, 3
	s_cmpk_gt_i32 s8, 0x1aff
	s_cbranch_scc1 .LBB0_158
	s_lshl_b32 s0, s89, 14
	v_lshrrev_b32_e32 v28, 5, v227
	v_and_b32_e32 v0, 31, v226
	s_add_i32 s0, s0, 0
	v_lshlrev_b32_e32 v20, 2, v0
	v_mul_u32_u24_e32 v0, 0x84, v28
	v_add3_u32 v29, s0, v20, v0
	v_lshlrev_b32_e32 v0, 3, v226
	v_and_b32_e32 v0, 56, v0
	v_readlane_b32 s12, v254, 13
	v_mul_u32_u24_e32 v4, 0x84, v0
	v_lshlrev_b32_e32 v0, 1, v0
	v_mov_b32_e32 v1, 0
	v_readlane_b32 s16, v254, 17
	v_lshrrev_b32_e32 v30, 3, v227
	v_lshl_add_u64 v[10:11], s[96:97], 0, v[0:1]
	s_mov_b64 s[2:3], 0x2900000
	v_readlane_b32 s13, v254, 14
	v_readlane_b32 s17, v254, 18
	s_add_u32 s12, s16, 0x1000
	v_lshl_add_u64 v[2:3], v[10:11], 0, s[2:3]
	v_lshlrev_b32_e32 v0, 2, v30
	s_mov_b64 s[2:3], 0x1900000
	v_readlane_b32 s18, v254, 19
	v_readlane_b32 s19, v254, 20
	s_addc_u32 s13, s17, 0
	v_add3_u32 v31, s0, v4, v0
	v_lshl_add_u64 v[4:5], v[10:11], 0, s[2:3]
	s_mov_b64 s[2:3], 0x900000
	v_readlane_b32 s14, v254, 15
	v_readlane_b32 s15, v254, 16
	s_cmp_lg_u64 s[18:19], 0
	v_lshl_add_u64 v[6:7], v[10:11], 0, s[2:3]
	s_mov_b64 s[2:3], 0x700000
	s_cselect_b64 s[14:15], -1, 0
	s_cmp_lg_u64 s[16:17], 0
	v_lshl_add_u64 v[8:9], v[10:11], 0, s[2:3]
	s_mov_b64 s[2:3], 0x100000
	v_mov_b32_e32 v21, v1
	v_readlane_b32 s20, v254, 21
	v_readlane_b32 s21, v254, 22
	v_readlane_b32 s22, v254, 23
	v_readlane_b32 s23, v254, 24
	v_readlane_b32 s24, v254, 25
	v_readlane_b32 s25, v254, 26
	v_readlane_b32 s26, v254, 27
	v_readlane_b32 s27, v254, 28
	s_cselect_b64 s[16:17], -1, 0
	s_lshl_b32 s0, s8, 1
	s_mov_b32 s1, 0
	v_or_b32_e32 v32, 8, v30
	v_or_b32_e32 v33, 16, v30
	v_or_b32_e32 v34, 24, v30
	v_lshl_add_u64 v[10:11], v[10:11], 0, s[2:3]
	s_waitcnt lgkmcnt(0)
	v_lshl_add_u64 v[12:13], s[78:79], 0, v[20:21]
	v_lshl_add_u64 v[14:15], s[22:23], 0, v[20:21]
	v_lshl_add_u64 v[16:17], s[20:21], 0, v[20:21]
	v_lshl_add_u64 v[18:19], s[26:27], 0, v[20:21]
	v_lshl_add_u64 v[20:21], s[24:25], 0, v[20:21]
	s_lshl_b32 s9, s8, 5
	s_lshl_b32 s11, s10, 5
	s_lshl_b32 s20, s8, 7
	s_lshl_b32 s21, s10, 7
	s_lshl_b32 s22, s8, 4
	s_lshl_b32 s23, s10, 4
	s_mov_b32 s24, 0x1e000
	s_add_i32 s25, s0, 0x1e000
	s_lshl_b32 s26, s10, 1
	s_movk_i32 s27, 0x1800
	s_movk_i32 s28, 0x3000
	v_add_u32_e32 v35, 0x400, v29
	v_add_u32_e32 v36, 0x800, v29
	v_add_u32_e32 v37, 0xc00, v29
	v_add_u32_e32 v38, 0x1000, v29
	v_add_u32_e32 v39, 0x1400, v29
	v_add_u32_e32 v40, 0x1800, v29
	v_add_u32_e32 v41, 0x1c00, v29
	v_mov_b32_e32 v42, 0x8000
	v_mov_b32_e32 v43, 0x10000
	v_mov_b32_e32 v44, 0x18000
	v_mov_b32_e32 v45, 0x20000
	v_mov_b32_e32 v46, 0x28000
	v_mov_b32_e32 v47, 0x30000
	v_mov_b32_e32 v48, 0x38000
	v_mov_b32_e32 v49, 0x40000
	v_mov_b32_e32 v50, 0x48000
	v_mov_b32_e32 v51, 0x50000
	v_mov_b32_e32 v52, 0x58000
	v_mov_b32_e32 v53, 0x60000
	v_mov_b32_e32 v54, 0x68000
	v_mov_b32_e32 v55, 0x70000
	v_mov_b32_e32 v56, 0x78000
	v_mov_b32_e32 v57, 0x80000
	v_mov_b32_e32 v58, 0x88000
	v_mov_b32_e32 v59, 0x90000
	v_mov_b32_e32 v60, 0x98000
	v_mov_b32_e32 v61, 0xa0000
	v_mov_b32_e32 v62, 0xa8000
	v_mov_b32_e32 v63, 0xb0000
	s_mov_b32 s29, s8
	v_mov_b32_e32 v64, 0xb8000
	v_mov_b32_e32 v65, 0xc0000
	v_mov_b32_e32 v66, 0xc8000
	v_mov_b32_e32 v67, 0xd0000
	v_mov_b32_e32 v68, 0xd8000
	v_mov_b32_e32 v69, 0xe0000
	v_mov_b32_e32 v70, 0xe8000
	v_mov_b32_e32 v71, 0xf0000
	v_mov_b32_e32 v72, 0xf8000
	s_branch .LBB0_15

.LBB0_163:
	s_cmp_eq_u32 s99, 2
	s_cbranch_scc1 .Lp0_done
	v_lshl_add_u32 v0, s88, 9, v226
	s_mov_b32 s0, 0xc000
	s_lshl_b32 s2, s90, 9
	v_cmp_gt_i32_e32 vcc, s0, v0
	s_and_saveexec_b64 s[4:5], vcc
	s_cbranch_execz .LBB0_171
	v_cvt_f32_u32_e32 v2, s2
	v_add_u32_e32 v1, s2, v0
	v_mov_b32_e32 v3, s2
	v_cmp_gt_i32_e32 vcc, s0, v1
	v_rcp_iflag_f32_e32 v2, v2
	s_sub_i32 s3, 0, s2
	v_max_i32_e32 v4, 0xc000, v1
	v_addc_co_u32_e64 v3, s[0:1], v0, v3, vcc
	v_mul_f32_e32 v2, 0x4f7ffffe, v2
	v_cvt_u32_f32_e32 v2, v2
	v_sub_u32_e32 v3, v4, v3
	v_mul_lo_u32 v4, s3, v2
	v_mul_hi_u32 v4, v2, v4
	v_add_u32_e32 v2, v2, v4
	v_mul_hi_u32 v2, v3, v2
	v_mul_lo_u32 v4, v2, s2
	v_sub_u32_e32 v3, v3, v4
	v_add_u32_e32 v5, 1, v2
	v_cmp_le_u32_e64 s[0:1], s2, v3
	v_subrev_u32_e32 v4, s2, v3
	s_nop 0
	v_cndmask_b32_e64 v2, v2, v5, s[0:1]
	v_cndmask_b32_e64 v3, v3, v4, s[0:1]
	v_add_u32_e32 v4, 1, v2
	v_cmp_le_u32_e64 s[0:1], s2, v3
	s_nop 1
	v_cndmask_b32_e64 v2, v2, v4, s[0:1]
	v_addc_co_u32_e32 v4, vcc, 1, v2, vcc
	v_cmp_lt_u32_e32 vcc, 1, v4
	s_mov_b64 s[0:1], -1
	v_mov_b32_e32 v2, v0
	s_and_saveexec_b64 s[8:9], vcc
	s_cbranch_execz .LBB0_168
	v_and_b32_e32 v5, -2, v4
	s_lshl_b32 s3, s90, 10
	s_mov_b32 s12, s3
	s_mov_b64 s[10:11], 0
	v_mov_b32_e32 v6, 0
	v_mov_b32_e32 v7, v5
	v_mov_b64_e32 v[2:3], v[0:1]

.LBB0_182:
	s_or_b64 exec, exec, s[0:1]
	s_cmp_eq_u32 s99, 1
	s_cbranch_scc0 .Lp0_done
	s_mov_b32 s99, 2
	s_branch .Lp0_front
.Lp0_done:
	s_waitcnt lgkmcnt(0)
	s_barrier
